# weight-conversion prologue: second gain-load group of each tile issued together with the first (half the load waits)
# baseline (speedup 1.0000x reference)
.LBB0_1193:
	v_cndmask_b32_e64 v16, 0, 1, s[8:9]
	v_cmp_ne_u32_e64 s[4:5], 1, v16
	s_andn2_b64 vcc, exec, s[8:9]
	ds_write_b32 v18, v3 offset:14560
	s_cbranch_vccnz .LBB0_1202
	s_and_b64 vcc, exec, s[6:7]
	s_cbranch_vccnz .LBB0_1223
	v_add_u32_e32 v16, s16, v2
	v_ashrrev_i32_e32 v17, 31, v16
	v_lshl_add_u64 v[16:17], v[16:17], 2, s[2:3]
	global_load_dword v3, v[16:17], off
	global_load_dword v19, v[16:17], off offset:32
	global_load_dword v32, v[16:17], off offset:64
	global_load_dword v33, v[16:17], off offset:96
	global_load_dword v108, v[16:17], off offset:128
	global_load_dword v109, v[16:17], off offset:160
	global_load_dword v110, v[16:17], off offset:192
	global_load_dword v111, v[16:17], off offset:224
	s_waitcnt vmcnt(7)
	v_mul_f32_e32 v3, v31, v3
	s_waitcnt vmcnt(6)
	v_mul_f32_e32 v19, v30, v19
	ds_write_b32 v18, v3 offset:16640
	ds_write_b32 v18, v19 offset:18720
	s_waitcnt vmcnt(4)
	v_pk_mul_f32 v[16:17], v[14:15], v[32:33]
	s_cbranch_execnz .LBB0_1197

.LBB0_1197:
	s_and_b64 vcc, exec, s[6:7]
	ds_write_b32 v18, v16 offset:20800
	ds_write_b32 v18, v17 offset:22880
	s_cbranch_vccnz .LBB0_1224
	s_ashr_i32 s17, s16, 31
	v_ashrrev_i32_e32 v3, 31, v2
	v_lshl_add_u64 v[14:15], v[2:3], 0, s[16:17]
	v_lshl_add_u64 v[14:15], v[14:15], 2, s[2:3]
	s_waitcnt vmcnt(3)
	v_mul_f32_e32 v3, v27, v108
	s_waitcnt vmcnt(2)
	v_mul_f32_e32 v19, v26, v109
	ds_write_b32 v18, v3 offset:24960
	ds_write_b32 v18, v19 offset:27040
	s_waitcnt vmcnt(0)
	v_pk_mul_f32 v[14:15], v[10:11], v[110:111]
	s_cbranch_execnz .LBB0_1200

.LBB0_1203:
	s_and_b64 vcc, exec, s[6:7]
	s_cbranch_vccnz .LBB0_1225
	v_add_u32_e32 v10, s14, v2
	v_ashrrev_i32_e32 v11, 31, v10
	v_lshl_add_u64 v[10:11], v[10:11], 2, s[2:3]
	global_load_dword v3, v[10:11], off
	global_load_dword v16, v[10:11], off offset:32
	global_load_dword v14, v[10:11], off offset:64
	global_load_dword v15, v[10:11], off offset:96
	global_load_dword v112, v[10:11], off offset:128
	global_load_dword v113, v[10:11], off offset:160
	global_load_dword v114, v[10:11], off offset:192
	global_load_dword v115, v[10:11], off offset:224
	s_waitcnt vmcnt(7)
	v_mul_f32_e32 v3, v29, v3
	s_waitcnt vmcnt(6)
	v_mul_f32_e32 v16, v28, v16
	ds_write_b32 v18, v3 offset:33280
	ds_write_b32 v18, v16 offset:35360
	s_waitcnt vmcnt(4)
	v_pk_mul_f32 v[10:11], v[12:13], v[14:15]
	s_cbranch_execnz .LBB0_1206

.LBB0_1206:
	s_and_b64 vcc, exec, s[6:7]
	ds_write_b32 v18, v10 offset:37440
	ds_write_b32 v18, v11 offset:39520
	s_cbranch_vccnz .LBB0_1226
	s_ashr_i32 s15, s14, 31
	v_ashrrev_i32_e32 v3, 31, v2
	v_lshl_add_u64 v[10:11], v[2:3], 0, s[14:15]
	v_lshl_add_u64 v[10:11], v[10:11], 2, s[2:3]
	s_waitcnt vmcnt(3)
	v_mul_f32_e32 v3, v23, v112
	s_waitcnt vmcnt(2)
	v_mul_f32_e32 v14, v22, v113
	ds_write_b32 v18, v3 offset:41600
	ds_write_b32 v18, v14 offset:43680
	s_waitcnt vmcnt(0)
	v_pk_mul_f32 v[10:11], v[6:7], v[114:115]
	s_cbranch_execnz .LBB0_1209

.LBB0_1210:
	s_and_b64 vcc, exec, s[6:7]
	s_cbranch_vccnz .LBB0_1227
	v_add_u32_e32 v6, s12, v2
	v_ashrrev_i32_e32 v7, 31, v6
	v_lshl_add_u64 v[6:7], v[6:7], 2, s[2:3]
	global_load_dword v3, v[6:7], off
	global_load_dword v12, v[6:7], off offset:32
	global_load_dword v10, v[6:7], off offset:64
	global_load_dword v11, v[6:7], off offset:96
	global_load_dword v116, v[6:7], off offset:128
	global_load_dword v117, v[6:7], off offset:160
	global_load_dword v118, v[6:7], off offset:192
	global_load_dword v119, v[6:7], off offset:224
	s_waitcnt vmcnt(7)
	v_mul_f32_e32 v3, v25, v3
	s_waitcnt vmcnt(6)
	v_mul_f32_e32 v12, v24, v12
	ds_write_b32 v18, v3 offset:49920
	ds_write_b32 v18, v12 offset:52000
	s_waitcnt vmcnt(4)
	v_pk_mul_f32 v[6:7], v[8:9], v[10:11]
	s_cbranch_execnz .LBB0_1213

.LBB0_1213:
	s_and_b64 vcc, exec, s[6:7]
	ds_write_b32 v18, v6 offset:54080
	ds_write_b32 v18, v7 offset:56160
	s_cbranch_vccnz .LBB0_1228
	s_ashr_i32 s13, s12, 31
	v_ashrrev_i32_e32 v3, 31, v2
	v_lshl_add_u64 v[2:3], v[2:3], 0, s[12:13]
	v_lshl_add_u64 v[2:3], v[2:3], 2, s[2:3]
	s_waitcnt vmcnt(3)
	v_mul_f32_e32 v8, v21, v116
	s_waitcnt vmcnt(2)
	v_mul_f32_e32 v9, v20, v117
	ds_write_b32 v18, v8 offset:58240
	ds_write_b32 v18, v9 offset:60320
	s_waitcnt vmcnt(0)
	v_pk_mul_f32 v[2:3], v[4:5], v[118:119]
	s_cbranch_execnz .LBB0_1216
